# attention QK (first half of the unrolled pair): third K fragment pair read two MFMAs earlier into the free transposed-read registers, counted waits
# baseline (speedup 1.0000x reference)
.LBB0_215:
	v_lshl_add_u64 v[150:151], v[148:149], 0, s[58:59]
	ds_read_b128 v[64:67], v181 offset:49152
	ds_read_b128 v[68:71], v181 offset:57344
	v_add_f32_e32 v128, 0, v234
	v_add_f32_e32 v128, v235, v128
	v_add_f32_e32 v128, v236, v128
	s_waitcnt lgkmcnt(1)
	v_mfma_f32_32x32x16_bf16 v[80:95], v[64:67], v[108:111], 0
	v_add_f32_e32 v128, v237, v128
	v_add_f32_e32 v128, v238, v128
	ds_read_b128 v[202:205], v182 offset:49152
	ds_read_b128 v[206:209], v182 offset:57344
	ds_read_b128 v[210:213], v183 offset:49152
	ds_read_b128 v[214:217], v183 offset:57344
	v_add_f32_e32 v128, v239, v128
	v_add_f32_e32 v128, v240, v128
	v_add_f32_e32 v128, v241, v128
	v_add_f32_e32 v128, v242, v128
	s_waitcnt lgkmcnt(4)
	v_mfma_f32_32x32x16_bf16 v[64:79], v[68:71], v[108:111], 0
	v_add_f32_e32 v128, v243, v128
	v_add_f32_e32 v128, v244, v128
	v_add_f32_e32 v128, v245, v128
	v_add_f32_e32 v128, v246, v128
	v_add_f32_e32 v128, v247, v128
	v_add_f32_e32 v128, v252, v128
	v_add_f32_e32 v128, v253, v128
	s_waitcnt lgkmcnt(3)
	v_mfma_f32_32x32x16_bf16 v[80:95], v[202:205], v[104:107], v[80:95]
	v_add_f32_e32 v128, v218, v128
	v_add_f32_e32 v128, v219, v128
	v_add_f32_e32 v128, v220, v128
	v_add_f32_e32 v128, v221, v128
	v_add_f32_e32 v128, v222, v128
	v_add_f32_e32 v128, v223, v128
	v_add_f32_e32 v128, v224, v128
	s_waitcnt lgkmcnt(2)
	v_mfma_f32_32x32x16_bf16 v[64:79], v[206:209], v[104:107], v[64:79]
	ds_read_b128 v[202:205], v184 offset:49152
	ds_read_b128 v[206:209], v184 offset:57344
	v_add_f32_e32 v128, v225, v128
	v_add_f32_e32 v128, v226, v128
	v_add_f32_e32 v128, v227, v128
	v_add_f32_e32 v128, v228, v128
	v_add_f32_e32 v128, v229, v128
	v_add_f32_e32 v128, v230, v128
	s_waitcnt lgkmcnt(3)
	v_mfma_f32_32x32x16_bf16 v[80:95], v[210:213], v[100:103], v[80:95]
	v_add_f32_e32 v128, v231, v128
	v_add_f32_e32 v128, v232, v128
	v_add_f32_e32 v187, v233, v128
	v_mov_b32_e32 v188, v187
	v_lshl_add_u64 v[152:153], v[146:147], 0, s[58:59]
	s_nop 0
	v_permlane32_swap_b32_e32 v187, v188
	s_waitcnt lgkmcnt(2)
	v_mfma_f32_32x32x16_bf16 v[64:79], v[214:217], v[100:103], v[64:79]
	v_cvt_pk_bf16_f32 v128, v234, v235
	v_cvt_pk_bf16_f32 v129, v236, v237
	v_cvt_pk_bf16_f32 v130, v238, v239
	v_cvt_pk_bf16_f32 v131, v240, v241
	v_cvt_pk_bf16_f32 v198, v242, v243
	v_cvt_pk_bf16_f32 v199, v244, v245
	s_waitcnt lgkmcnt(1)
	v_mfma_f32_32x32x16_bf16 v[80:95], v[202:205], v[96:99], v[80:95]
	v_permlane32_swap_b32_e32 v128, v130
	v_cvt_pk_bf16_f32 v200, v246, v247
	v_cvt_pk_bf16_f32 v201, v252, v253
	v_cvt_pk_bf16_f32 v190, v218, v219
	v_cvt_pk_bf16_f32 v191, v220, v221
	v_cvt_pk_bf16_f32 v192, v222, v223
	s_waitcnt lgkmcnt(0)
	v_mfma_f32_32x32x16_bf16 v[64:79], v[206:209], v[96:99], v[64:79]
	v_add_co_u32_e32 v116, vcc, s86, v152
	s_nop 1
	v_addc_co_u32_e32 v117, vcc, 0, v153, vcc
	v_add_co_u32_e32 v120, vcc, s86, v150
	s_nop 1
	v_addc_co_u32_e32 v121, vcc, 0, v151, vcc
	ds_read_b64_tr_b16 v[202:203], v177 offset:0
	ds_read_b64_tr_b16 v[204:205], v177 offset:0x800
	ds_read_b64_tr_b16 v[206:207], v177 offset:0x1000
	ds_read_b64_tr_b16 v[208:209], v177 offset:0x1800
	ds_read_b64_tr_b16 v[210:211], v177 offset:0x2000
	ds_read_b64_tr_b16 v[212:213], v177 offset:0x2800
	ds_read_b64_tr_b16 v[214:215], v177 offset:0x3000
	ds_read_b64_tr_b16 v[216:217], v177 offset:0x3800
	v_cvt_pk_bf16_f32 v193, v224, v225
	v_cvt_pk_bf16_f32 v194, v226, v227
	v_cvt_pk_bf16_f32 v195, v228, v229
	v_cvt_pk_bf16_f32 v196, v230, v231
	v_cvt_pk_bf16_f32 v197, v232, v233
	v_permlane32_swap_b32_e32 v129, v131
	v_permlane32_swap_b32_e32 v198, v200
	v_permlane32_swap_b32_e32 v199, v201
	v_permlane32_swap_b32_e32 v190, v192
	v_permlane32_swap_b32_e32 v191, v193
	v_permlane32_swap_b32_e32 v194, v196
	v_permlane32_swap_b32_e32 v195, v197
	global_load_dwordx4 v[112:115], v[116:117], off offset:1024
	s_nop 0
	global_load_dwordx4 v[116:119], v[116:117], off
	s_nop 0
	global_load_dwordx4 v[124:127], v[120:121], off offset:1024
	s_nop 0
	global_load_dwordx4 v[120:123], v[120:121], off
	s_nop 0
	s_waitcnt lgkmcnt(6)
	v_mfma_f32_32x32x16_bf16 v[0:15], v[128:131], v[202:205], v[0:15]
	ds_read_b64_tr_b16 v[202:203], v177 offset:0x200
	ds_read_b64_tr_b16 v[204:205], v177 offset:0xa00
	v_max_f32_e32 v250, v80, v81
	v_max3_f32 v250, v250, v82, v83
	v_max3_f32 v250, v250, v84, v85
	v_max3_f32 v250, v250, v86, v87
	v_max3_f32 v250, v250, v88, v89
	v_max3_f32 v250, v250, v90, v91
	v_max3_f32 v250, v250, v92, v93
	s_waitcnt lgkmcnt(6)
	v_mfma_f32_32x32x16_bf16 v[0:15], v[198:201], v[206:209], v[0:15]
	ds_read_b64_tr_b16 v[206:207], v177 offset:0x1200
	ds_read_b64_tr_b16 v[208:209], v177 offset:0x1a00
	v_max3_f32 v250, v250, v94, v95
	v_max3_f32 v250, v250, v64, v65
	v_max3_f32 v250, v250, v66, v67
	v_max3_f32 v250, v250, v68, v69
	v_max3_f32 v250, v250, v70, v71
	v_max3_f32 v250, v250, v72, v73
	v_max3_f32 v250, v250, v74, v75
	v_max3_f32 v250, v250, v76, v77
	v_max3_f32 v250, v250, v78, v79
	s_waitcnt lgkmcnt(6)
	v_mfma_f32_32x32x16_bf16 v[0:15], v[190:193], v[210:213], v[0:15]
	ds_read_b64_tr_b16 v[210:211], v177 offset:0x2200
	ds_read_b64_tr_b16 v[212:213], v177 offset:0x2a00
	v_mov_b32_e32 v251, v250
	s_nop 1
	v_permlane32_swap_b32_e32 v250, v251
	v_max_f32_e32 v250, v250, v251
	v_sub_f32_e32 v251, v250, v186
	v_cmp_ge_f32_e32 vcc, s33, v251
	v_max_f32_e32 v251, v186, v186
	v_max_f32_e32 v250, v251, v250
	s_waitcnt lgkmcnt(6)
	v_mfma_f32_32x32x16_bf16 v[0:15], v[194:197], v[214:217], v[0:15]
	ds_read_b64_tr_b16 v[214:215], v177 offset:0x3200
	ds_read_b64_tr_b16 v[216:217], v177 offset:0x3a00
	v_sub_f32_e32 v251, v186, v250
	v_mul_f32_e32 v251, 0x3e38aa3b, v251
	v_exp_f32_e32 v251, v251
	s_cmp_eq_u64 vcc, exec
	s_cselect_b64 s[6:7], -1, 0
	v_cndmask_b32_e64 v186, v250, v186, s[6:7]
	v_mul_f32_e32 v254, 0xbe38aa3b, v186
	s_waitcnt lgkmcnt(6)
	v_mfma_f32_32x32x16_bf16 v[48:63], v[128:131], v[202:205], v[48:63]
	ds_read_b64_tr_b16 v[202:203], v177 offset:0x400
	ds_read_b64_tr_b16 v[204:205], v177 offset:0xc00
	v_fmamk_f32 v80, v80, 0x3e38aa3b, v254
	v_fmamk_f32 v81, v81, 0x3e38aa3b, v254
	v_fmamk_f32 v64, v64, 0x3e38aa3b, v254
	v_fmamk_f32 v65, v65, 0x3e38aa3b, v254
	v_exp_f32_e32 v234, v80
	v_exp_f32_e32 v235, v81
	v_fmamk_f32 v82, v82, 0x3e38aa3b, v254
	v_fmamk_f32 v83, v83, 0x3e38aa3b, v254
	s_waitcnt lgkmcnt(6)
	v_mfma_f32_32x32x16_bf16 v[48:63], v[198:201], v[206:209], v[48:63]
	ds_read_b64_tr_b16 v[206:207], v177 offset:0x1400
	ds_read_b64_tr_b16 v[208:209], v177 offset:0x1c00
	v_exp_f32_e32 v218, v64
	v_exp_f32_e32 v219, v65
	v_fmamk_f32 v66, v66, 0x3e38aa3b, v254
	v_fmamk_f32 v67, v67, 0x3e38aa3b, v254
	v_exp_f32_e32 v236, v82
	s_waitcnt lgkmcnt(6)
	v_mfma_f32_32x32x16_bf16 v[48:63], v[190:193], v[210:213], v[48:63]
	ds_read_b64_tr_b16 v[210:211], v177 offset:0x2400
	ds_read_b64_tr_b16 v[212:213], v177 offset:0x2c00
	v_exp_f32_e32 v237, v83
	v_fmamk_f32 v84, v84, 0x3e38aa3b, v254
	v_fmamk_f32 v85, v85, 0x3e38aa3b, v254
	v_exp_f32_e32 v220, v66
	v_exp_f32_e32 v221, v67
	s_waitcnt lgkmcnt(6)
	v_mfma_f32_32x32x16_bf16 v[48:63], v[194:197], v[214:217], v[48:63]
	ds_read_b64_tr_b16 v[214:215], v177 offset:0x3400
	ds_read_b64_tr_b16 v[216:217], v177 offset:0x3c00
	v_fmamk_f32 v68, v68, 0x3e38aa3b, v254
	v_fmamk_f32 v69, v69, 0x3e38aa3b, v254
	v_exp_f32_e32 v238, v84
	v_exp_f32_e32 v239, v85
	v_fmamk_f32 v86, v86, 0x3e38aa3b, v254
	v_fmamk_f32 v87, v87, 0x3e38aa3b, v254
	s_waitcnt lgkmcnt(6)
	v_mfma_f32_32x32x16_bf16 v[32:47], v[128:131], v[202:205], v[32:47]
	ds_read_b64_tr_b16 v[202:203], v177 offset:0x600
	ds_read_b64_tr_b16 v[204:205], v177 offset:0xe00
	v_exp_f32_e32 v222, v68
	v_exp_f32_e32 v223, v69
	v_fmamk_f32 v70, v70, 0x3e38aa3b, v254
	v_fmamk_f32 v71, v71, 0x3e38aa3b, v254
	v_exp_f32_e32 v240, v86
	s_waitcnt lgkmcnt(6)
	v_mfma_f32_32x32x16_bf16 v[32:47], v[198:201], v[206:209], v[32:47]
	ds_read_b64_tr_b16 v[206:207], v177 offset:0x1600
	ds_read_b64_tr_b16 v[208:209], v177 offset:0x1e00
	v_exp_f32_e32 v241, v87
	v_fmamk_f32 v88, v88, 0x3e38aa3b, v254
	v_fmamk_f32 v89, v89, 0x3e38aa3b, v254
	v_exp_f32_e32 v224, v70
	v_exp_f32_e32 v225, v71
	s_waitcnt lgkmcnt(6)
	v_mfma_f32_32x32x16_bf16 v[32:47], v[190:193], v[210:213], v[32:47]
	ds_read_b64_tr_b16 v[210:211], v177 offset:0x2600
	ds_read_b64_tr_b16 v[212:213], v177 offset:0x2e00
	v_fmamk_f32 v72, v72, 0x3e38aa3b, v254
	v_fmamk_f32 v73, v73, 0x3e38aa3b, v254
	v_exp_f32_e32 v242, v88
	v_exp_f32_e32 v243, v89
	v_fmamk_f32 v90, v90, 0x3e38aa3b, v254
	v_fmamk_f32 v91, v91, 0x3e38aa3b, v254
	s_waitcnt lgkmcnt(6)
	v_mfma_f32_32x32x16_bf16 v[32:47], v[194:197], v[214:217], v[32:47]
	ds_read_b64_tr_b16 v[214:215], v177 offset:0x3600
	ds_read_b64_tr_b16 v[216:217], v177 offset:0x3e00
	v_exp_f32_e32 v226, v72
	v_exp_f32_e32 v227, v73
	v_fmamk_f32 v74, v74, 0x3e38aa3b, v254
	v_fmamk_f32 v75, v75, 0x3e38aa3b, v254
	v_exp_f32_e32 v244, v90
	s_waitcnt lgkmcnt(6)
	v_mfma_f32_32x32x16_bf16 v[16:31], v[128:131], v[202:205], v[16:31]
	v_exp_f32_e32 v245, v91
	v_fmamk_f32 v92, v92, 0x3e38aa3b, v254
	v_fmamk_f32 v93, v93, 0x3e38aa3b, v254
	v_exp_f32_e32 v228, v74
	v_exp_f32_e32 v229, v75
	s_waitcnt lgkmcnt(4)
	v_mfma_f32_32x32x16_bf16 v[16:31], v[198:201], v[206:209], v[16:31]
	v_fmamk_f32 v76, v76, 0x3e38aa3b, v254
	v_fmamk_f32 v77, v77, 0x3e38aa3b, v254
	v_exp_f32_e32 v246, v92
	v_exp_f32_e32 v247, v93
	v_fmamk_f32 v94, v94, 0x3e38aa3b, v254
	v_fmamk_f32 v95, v95, 0x3e38aa3b, v254
	s_waitcnt lgkmcnt(2)
	v_mfma_f32_32x32x16_bf16 v[16:31], v[190:193], v[210:213], v[16:31]
	v_exp_f32_e32 v230, v76
	v_exp_f32_e32 v231, v77
	v_fmamk_f32 v78, v78, 0x3e38aa3b, v254
	v_fmamk_f32 v79, v79, 0x3e38aa3b, v254
	v_exp_f32_e32 v252, v94
	s_waitcnt lgkmcnt(0)
	v_mfma_f32_32x32x16_bf16 v[16:31], v[194:197], v[214:217], v[16:31]
	v_exp_f32_e32 v253, v95
	s_nop 0
	v_exp_f32_e32 v232, v78
	v_exp_f32_e32 v233, v79
	s_barrier
	s_waitcnt vmcnt(0)
	v_cndmask_b32_e64 v202, v251, 1.0, s[6:7]
	v_cmp_gt_f32_e32 vcc, 1.0, v202
	s_waitcnt vmcnt(3)
	ds_write_b128 v134, v[112:115]
	s_waitcnt vmcnt(1)
	ds_write_b128 v145, v[124:127]
	ds_write_b128 v175, v[116:119] offset:32768
	s_waitcnt vmcnt(0)
	ds_write_b128 v180, v[120:123] offset:32768
	s_cbranch_vccz .LBB0_219
	s_and_saveexec_b64 s[60:61], s[4:5]
	ds_write_b32 v176, v202 offset:128
	s_or_b64 exec, exec, s[60:61]
	s_waitcnt lgkmcnt(0)
	v_add_u32_e32 v124, v174, v144
	ds_read_b128 v[112:115], v124 offset:224
	ds_read_b128 v[116:119], v124 offset:192
	ds_read_b128 v[120:123], v124 offset:160
	ds_read_b128 v[124:127], v124 offset:128
	s_waitcnt lgkmcnt(3)
	v_pk_mul_f32 v[12:13], v[12:13], v[112:113]
	s_waitcnt lgkmcnt(2)
	v_pk_mul_f32 v[8:9], v[8:9], v[116:117]
	s_waitcnt lgkmcnt(1)
	v_pk_mul_f32 v[4:5], v[4:5], v[120:121]
	v_pk_mul_f32 v[14:15], v[14:15], v[114:115]
	v_pk_mul_f32 v[10:11], v[10:11], v[118:119]
	v_pk_mul_f32 v[6:7], v[6:7], v[122:123]
	s_waitcnt lgkmcnt(0)
	v_pk_mul_f32 v[2:3], v[2:3], v[126:127]
	v_pk_mul_f32 v[0:1], v[0:1], v[124:125]
	v_pk_mul_f32 v[60:61], v[60:61], v[112:113]
	v_pk_mul_f32 v[56:57], v[56:57], v[116:117]
	v_pk_mul_f32 v[52:53], v[52:53], v[120:121]
	v_pk_mul_f32 v[62:63], v[62:63], v[114:115]
	v_pk_mul_f32 v[58:59], v[58:59], v[118:119]
	v_pk_mul_f32 v[54:55], v[54:55], v[122:123]
	v_pk_mul_f32 v[50:51], v[50:51], v[126:127]
	v_pk_mul_f32 v[48:49], v[48:49], v[124:125]
	v_pk_mul_f32 v[44:45], v[44:45], v[112:113]
	v_pk_mul_f32 v[40:41], v[40:41], v[116:117]
	v_pk_mul_f32 v[36:37], v[36:37], v[120:121]
	v_pk_mul_f32 v[46:47], v[46:47], v[114:115]
	v_pk_mul_f32 v[42:43], v[42:43], v[118:119]
	v_pk_mul_f32 v[38:39], v[38:39], v[122:123]
	v_pk_mul_f32 v[34:35], v[34:35], v[126:127]
	v_pk_mul_f32 v[32:33], v[32:33], v[124:125]
	v_pk_mul_f32 v[28:29], v[28:29], v[112:113]
	v_pk_mul_f32 v[24:25], v[24:25], v[116:117]
	v_pk_mul_f32 v[20:21], v[20:21], v[120:121]
	v_pk_mul_f32 v[30:31], v[30:31], v[114:115]
	v_pk_mul_f32 v[26:27], v[26:27], v[118:119]
	v_pk_mul_f32 v[22:23], v[22:23], v[122:123]
	v_pk_mul_f32 v[18:19], v[18:19], v[126:127]
	v_pk_mul_f32 v[16:17], v[16:17], v[124:125]
